# OUT epilogue: per-step vmcnt waits relaxed from vmcnt(7) to vmcnt(7+k) (exact lower bound of younger ops: remaining loads + one store and one atomic per earlier step)
# baseline (speedup 1.0000x reference)
.LBB0_1010:
	s_or_b64 exec, exec, s[2:3]
	ds_read_b128 v[192:195], v229 offset:1088
	v_or_b32_e32 v128, v166, v200
	s_waitcnt lgkmcnt(1)
	v_ashrrev_i32_e32 v129, 31, v128
	v_lshlrev_b64 v[154:155], 10, v[128:129]
	v_lshl_add_u64 v[128:129], v[154:155], 0, v[164:165]
	s_waitcnt vmcnt(8) lgkmcnt(0)
	v_pk_fma_f32 v[124:125], v[136:137], v[194:195], v[124:125]
	v_pk_fma_f32 v[122:123], v[134:135], v[192:193], v[122:123]
	v_lshl_add_u64 v[176:177], v[128:129], 2, s[44:45]
	s_and_b64 vcc, exec, s[40:41]
	s_mov_b64 s[2:3], -1
	global_store_dwordx4 v[176:177], v[122:125], off
	s_cbranch_vccnz .LBB0_1012
	s_mov_b64 s[2:3], 0

.LBB0_1016:
	s_or_b64 exec, exec, s[2:3]
	ds_read_b128 v[192:195], v229 offset:2176
	v_or_b32_e32 v122, v166, v201
	s_waitcnt lgkmcnt(1)
	v_ashrrev_i32_e32 v123, 31, v122
	v_lshlrev_b64 v[128:129], 10, v[122:123]
	v_lshl_add_u64 v[122:123], v[128:129], 0, v[164:165]
	s_waitcnt vmcnt(9) lgkmcnt(0)
	v_pk_fma_f32 v[120:121], v[136:137], v[194:195], v[120:121]
	v_pk_fma_f32 v[118:119], v[134:135], v[192:193], v[118:119]
	v_lshl_add_u64 v[124:125], v[122:123], 2, s[44:45]
	s_and_b64 vcc, exec, s[40:41]
	s_mov_b64 s[2:3], -1
	global_store_dwordx4 v[124:125], v[118:121], off
	s_cbranch_vccnz .LBB0_1018
	s_mov_b64 s[2:3], 0

.LBB0_1022:
	s_or_b64 exec, exec, s[2:3]
	ds_read_b128 v[122:125], v229 offset:3264
	v_or_b32_e32 v118, v166, v202
	s_waitcnt lgkmcnt(1)
	v_ashrrev_i32_e32 v119, 31, v118
	v_lshlrev_b64 v[120:121], 10, v[118:119]
	v_lshl_add_u64 v[118:119], v[120:121], 0, v[164:165]
	s_waitcnt vmcnt(10) lgkmcnt(0)
	v_pk_fma_f32 v[116:117], v[136:137], v[124:125], v[116:117]
	v_pk_fma_f32 v[114:115], v[134:135], v[122:123], v[114:115]
	v_lshl_add_u64 v[122:123], v[118:119], 2, s[44:45]
	s_and_b64 vcc, exec, s[40:41]
	s_mov_b64 s[2:3], -1
	global_store_dwordx4 v[122:123], v[114:117], off
	s_cbranch_vccnz .LBB0_1024
	s_mov_b64 s[2:3], 0

.LBB0_1028:
	s_or_b64 exec, exec, s[2:3]
	ds_read_b128 v[122:125], v229 offset:4352
	v_or_b32_e32 v114, v166, v203
	s_waitcnt lgkmcnt(1)
	v_ashrrev_i32_e32 v115, 31, v114
	v_lshlrev_b64 v[114:115], 10, v[114:115]
	v_lshl_add_u64 v[116:117], v[114:115], 0, v[164:165]
	s_waitcnt vmcnt(11) lgkmcnt(0)
	v_pk_fma_f32 v[112:113], v[136:137], v[124:125], v[112:113]
	v_pk_fma_f32 v[110:111], v[134:135], v[122:123], v[110:111]
	v_lshl_add_u64 v[118:119], v[116:117], 2, s[44:45]
	s_and_b64 vcc, exec, s[40:41]
	s_mov_b64 s[2:3], -1
	global_store_dwordx4 v[118:119], v[110:113], off
	s_cbranch_vccnz .LBB0_1030
	s_mov_b64 s[2:3], 0

.LBB0_1034:
	s_or_b64 exec, exec, s[2:3]
	ds_read_b128 v[116:119], v229 offset:5440
	v_or_b32_e32 v110, v166, v204
	s_waitcnt lgkmcnt(1)
	v_ashrrev_i32_e32 v111, 31, v110
	v_lshlrev_b64 v[110:111], 10, v[110:111]
	v_lshl_add_u64 v[112:113], v[110:111], 0, v[164:165]
	s_waitcnt vmcnt(12) lgkmcnt(0)
	v_pk_fma_f32 v[108:109], v[136:137], v[118:119], v[108:109]
	v_pk_fma_f32 v[106:107], v[134:135], v[116:117], v[106:107]
	v_lshl_add_u64 v[116:117], v[112:113], 2, s[44:45]
	s_and_b64 vcc, exec, s[40:41]
	s_mov_b64 s[2:3], -1
	global_store_dwordx4 v[116:117], v[106:109], off
	s_cbranch_vccnz .LBB0_1036
	s_mov_b64 s[2:3], 0

.LBB0_1046:
	s_or_b64 exec, exec, s[2:3]
	ds_read_b128 v[116:119], v229 offset:7616
	v_or_b32_e32 v102, v166, v226
	s_waitcnt lgkmcnt(1)
	v_ashrrev_i32_e32 v103, 31, v102
	v_lshlrev_b64 v[102:103], 10, v[102:103]
	v_lshl_add_u64 v[104:105], v[102:103], 0, v[164:165]
	s_waitcnt vmcnt(14) lgkmcnt(0)
	v_pk_fma_f32 v[100:101], v[136:137], v[118:119], v[100:101]
	v_pk_fma_f32 v[98:99], v[134:135], v[116:117], v[98:99]
	v_lshl_add_u64 v[108:109], v[104:105], 2, s[44:45]
	s_and_b64 vcc, exec, s[40:41]
	s_mov_b64 s[2:3], -1
	global_store_dwordx4 v[108:109], v[98:101], off
	s_cbranch_vccnz .LBB0_1048
	s_mov_b64 s[2:3], 0

.LBB0_1058:
	s_or_b64 exec, exec, s[2:3]
	ds_read_b128 v[192:195], v229 offset:1088
	v_or_b32_e32 v94, v168, v200
	s_waitcnt lgkmcnt(1)
	v_ashrrev_i32_e32 v95, 31, v94
	v_lshlrev_b64 v[94:95], 10, v[94:95]
	v_lshl_add_u64 v[96:97], v[94:95], 0, v[164:165]
	s_waitcnt vmcnt(8) lgkmcnt(0)
	v_pk_fma_f32 v[92:93], v[136:137], v[194:195], v[92:93]
	v_pk_fma_f32 v[90:91], v[134:135], v[192:193], v[90:91]
	v_lshl_add_u64 v[166:167], v[96:97], 2, s[44:45]
	s_and_b64 vcc, exec, s[40:41]
	s_mov_b64 s[2:3], -1
	global_store_dwordx4 v[166:167], v[90:93], off
	s_cbranch_vccnz .LBB0_1060
	s_mov_b64 s[2:3], 0

.LBB0_1064:
	s_or_b64 exec, exec, s[2:3]
	ds_read_b128 v[192:195], v229 offset:2176
	v_or_b32_e32 v90, v168, v201
	s_waitcnt lgkmcnt(1)
	v_ashrrev_i32_e32 v91, 31, v90
	v_lshlrev_b64 v[90:91], 10, v[90:91]
	v_lshl_add_u64 v[92:93], v[90:91], 0, v[164:165]
	s_waitcnt vmcnt(9) lgkmcnt(0)
	v_pk_fma_f32 v[88:89], v[136:137], v[194:195], v[88:89]
	v_pk_fma_f32 v[86:87], v[134:135], v[192:193], v[86:87]
	v_lshl_add_u64 v[96:97], v[92:93], 2, s[44:45]
	s_and_b64 vcc, exec, s[40:41]
	s_mov_b64 s[2:3], -1
	global_store_dwordx4 v[96:97], v[86:89], off
	s_cbranch_vccnz .LBB0_1066
	s_mov_b64 s[2:3], 0

.LBB0_1070:
	s_or_b64 exec, exec, s[2:3]
	ds_read_b128 v[192:195], v229 offset:3264
	v_or_b32_e32 v86, v168, v202
	s_waitcnt lgkmcnt(1)
	v_ashrrev_i32_e32 v87, 31, v86
	v_lshlrev_b64 v[86:87], 10, v[86:87]
	v_lshl_add_u64 v[88:89], v[86:87], 0, v[164:165]
	s_waitcnt vmcnt(10) lgkmcnt(0)
	v_pk_fma_f32 v[84:85], v[136:137], v[194:195], v[84:85]
	v_pk_fma_f32 v[82:83], v[134:135], v[192:193], v[82:83]
	v_lshl_add_u64 v[92:93], v[88:89], 2, s[44:45]
	s_and_b64 vcc, exec, s[40:41]
	s_mov_b64 s[2:3], -1
	global_store_dwordx4 v[92:93], v[82:85], off
	s_cbranch_vccnz .LBB0_1072
	s_mov_b64 s[2:3], 0

.LBB0_1076:
	s_or_b64 exec, exec, s[2:3]
	ds_read_b128 v[192:195], v229 offset:4352
	v_or_b32_e32 v82, v168, v203
	s_waitcnt lgkmcnt(1)
	v_ashrrev_i32_e32 v83, 31, v82
	v_lshlrev_b64 v[82:83], 10, v[82:83]
	v_lshl_add_u64 v[84:85], v[82:83], 0, v[164:165]
	s_waitcnt vmcnt(11) lgkmcnt(0)
	v_pk_fma_f32 v[80:81], v[136:137], v[194:195], v[80:81]
	v_pk_fma_f32 v[78:79], v[134:135], v[192:193], v[78:79]
	v_lshl_add_u64 v[88:89], v[84:85], 2, s[44:45]
	s_and_b64 vcc, exec, s[40:41]
	s_mov_b64 s[2:3], -1
	global_store_dwordx4 v[88:89], v[78:81], off
	s_cbranch_vccnz .LBB0_1078
	s_mov_b64 s[2:3], 0

.LBB0_1082:
	s_or_b64 exec, exec, s[2:3]
	ds_read_b128 v[192:195], v229 offset:5440
	v_or_b32_e32 v78, v168, v204
	s_waitcnt lgkmcnt(1)
	v_ashrrev_i32_e32 v79, 31, v78
	v_lshlrev_b64 v[78:79], 10, v[78:79]
	v_lshl_add_u64 v[80:81], v[78:79], 0, v[164:165]
	s_waitcnt vmcnt(12) lgkmcnt(0)
	v_pk_fma_f32 v[76:77], v[136:137], v[194:195], v[76:77]
	v_pk_fma_f32 v[74:75], v[134:135], v[192:193], v[74:75]
	v_lshl_add_u64 v[84:85], v[80:81], 2, s[44:45]
	s_and_b64 vcc, exec, s[40:41]
	s_mov_b64 s[2:3], -1
	global_store_dwordx4 v[84:85], v[74:77], off
	s_cbranch_vccnz .LBB0_1084
	s_mov_b64 s[2:3], 0

.LBB0_1088:
	s_or_b64 exec, exec, s[2:3]
	ds_read_b128 v[192:195], v229 offset:6528
	v_or_b32_e32 v74, v168, v205
	s_waitcnt lgkmcnt(1)
	v_ashrrev_i32_e32 v75, 31, v74
	v_lshlrev_b64 v[74:75], 10, v[74:75]
	v_lshl_add_u64 v[76:77], v[74:75], 0, v[164:165]
	s_waitcnt vmcnt(13) lgkmcnt(0)
	v_pk_fma_f32 v[72:73], v[136:137], v[194:195], v[72:73]
	v_pk_fma_f32 v[70:71], v[134:135], v[192:193], v[70:71]
	v_lshl_add_u64 v[80:81], v[76:77], 2, s[44:45]
	s_and_b64 vcc, exec, s[40:41]
	s_mov_b64 s[2:3], -1
	global_store_dwordx4 v[80:81], v[70:73], off
	s_cbranch_vccnz .LBB0_1090
	s_mov_b64 s[2:3], 0

.LBB0_1094:
	s_or_b64 exec, exec, s[2:3]
	ds_read_b128 v[192:195], v229 offset:7616
	v_or_b32_e32 v70, v168, v226
	s_waitcnt lgkmcnt(1)
	v_ashrrev_i32_e32 v71, 31, v70
	v_lshlrev_b64 v[76:77], 10, v[70:71]
	v_lshl_add_u64 v[70:71], v[76:77], 0, v[164:165]
	s_waitcnt vmcnt(14) lgkmcnt(0)
	v_pk_fma_f32 v[68:69], v[136:137], v[194:195], v[68:69]
	v_pk_fma_f32 v[66:67], v[134:135], v[192:193], v[66:67]
	v_lshl_add_u64 v[72:73], v[70:71], 2, s[44:45]
	s_and_b64 vcc, exec, s[40:41]
	s_mov_b64 s[2:3], -1
	global_store_dwordx4 v[72:73], v[66:69], off
	s_cbranch_vccnz .LBB0_1096
	s_mov_b64 s[2:3], 0

.LBB0_1106:
	s_or_b64 exec, exec, s[2:3]
	s_waitcnt lgkmcnt(0)
	ds_read_b128 v[62:65], v229 offset:1088
	s_mov_b64 s[2:3], -1
	s_and_b64 vcc, exec, s[40:41]
	s_waitcnt vmcnt(8) lgkmcnt(0)
	v_pk_fma_f32 v[58:59], v[70:71], v[62:63], v[58:59]
	v_lshl_add_u64 v[62:63], v[154:155], 0, v[84:85]
	v_pk_fma_f32 v[60:61], v[72:73], v[64:65], v[60:61]
	v_lshl_add_u64 v[62:63], v[62:63], 2, s[44:45]
	global_store_dwordx4 v[62:63], v[58:61], off offset:256
	s_cbranch_vccnz .LBB0_1108
	s_mov_b64 s[2:3], 0

.LBB0_1112:
	s_or_b64 exec, exec, s[2:3]
	s_waitcnt lgkmcnt(0)
	ds_read_b128 v[58:61], v229 offset:2176
	s_mov_b64 s[2:3], -1
	s_and_b64 vcc, exec, s[40:41]
	s_waitcnt vmcnt(9) lgkmcnt(0)
	v_pk_fma_f32 v[54:55], v[70:71], v[58:59], v[54:55]
	v_lshl_add_u64 v[58:59], v[128:129], 0, v[84:85]
	v_pk_fma_f32 v[56:57], v[72:73], v[60:61], v[56:57]
	v_lshl_add_u64 v[58:59], v[58:59], 2, s[44:45]
	global_store_dwordx4 v[58:59], v[54:57], off offset:256
	s_cbranch_vccnz .LBB0_1114
	s_mov_b64 s[2:3], 0

.LBB0_1118:
	s_or_b64 exec, exec, s[2:3]
	s_waitcnt lgkmcnt(0)
	ds_read_b128 v[54:57], v229 offset:3264
	s_mov_b64 s[2:3], -1
	s_and_b64 vcc, exec, s[40:41]
	s_waitcnt vmcnt(10) lgkmcnt(0)
	v_pk_fma_f32 v[50:51], v[70:71], v[54:55], v[50:51]
	v_lshl_add_u64 v[54:55], v[120:121], 0, v[84:85]
	v_pk_fma_f32 v[52:53], v[72:73], v[56:57], v[52:53]
	v_lshl_add_u64 v[54:55], v[54:55], 2, s[44:45]
	global_store_dwordx4 v[54:55], v[50:53], off offset:256
	s_cbranch_vccnz .LBB0_1120
	s_mov_b64 s[2:3], 0

.LBB0_1124:
	s_or_b64 exec, exec, s[2:3]
	s_waitcnt lgkmcnt(0)
	ds_read_b128 v[50:53], v229 offset:4352
	s_mov_b64 s[2:3], -1
	s_and_b64 vcc, exec, s[40:41]
	s_waitcnt vmcnt(11) lgkmcnt(0)
	v_pk_fma_f32 v[46:47], v[70:71], v[50:51], v[46:47]
	v_lshl_add_u64 v[50:51], v[114:115], 0, v[84:85]
	v_pk_fma_f32 v[48:49], v[72:73], v[52:53], v[48:49]
	v_lshl_add_u64 v[50:51], v[50:51], 2, s[44:45]
	global_store_dwordx4 v[50:51], v[46:49], off offset:256
	s_cbranch_vccnz .LBB0_1126
	s_mov_b64 s[2:3], 0

.LBB0_1130:
	s_or_b64 exec, exec, s[2:3]
	s_waitcnt lgkmcnt(0)
	ds_read_b128 v[46:49], v229 offset:5440
	s_mov_b64 s[2:3], -1
	s_and_b64 vcc, exec, s[40:41]
	s_waitcnt vmcnt(12) lgkmcnt(0)
	v_pk_fma_f32 v[42:43], v[70:71], v[46:47], v[42:43]
	v_lshl_add_u64 v[46:47], v[110:111], 0, v[84:85]
	v_pk_fma_f32 v[44:45], v[72:73], v[48:49], v[44:45]
	v_lshl_add_u64 v[46:47], v[46:47], 2, s[44:45]
	global_store_dwordx4 v[46:47], v[42:45], off offset:256
	s_cbranch_vccnz .LBB0_1132
	s_mov_b64 s[2:3], 0

.LBB0_1142:
	s_or_b64 exec, exec, s[2:3]
	s_waitcnt lgkmcnt(0)
	ds_read_b128 v[38:41], v229 offset:7616
	s_mov_b64 s[2:3], -1
	s_and_b64 vcc, exec, s[40:41]
	s_waitcnt vmcnt(14) lgkmcnt(0)
	v_pk_fma_f32 v[34:35], v[70:71], v[38:39], v[34:35]
	v_lshl_add_u64 v[38:39], v[102:103], 0, v[84:85]
	v_pk_fma_f32 v[36:37], v[72:73], v[40:41], v[36:37]
	v_lshl_add_u64 v[38:39], v[38:39], 2, s[44:45]
	global_store_dwordx4 v[38:39], v[34:37], off offset:256
	s_cbranch_vccnz .LBB0_1144
	s_mov_b64 s[2:3], 0

.LBB0_1154:
	s_or_b64 exec, exec, s[2:3]
	s_waitcnt lgkmcnt(0)
	ds_read_b128 v[30:33], v229 offset:1088
	s_mov_b64 s[2:3], -1
	s_and_b64 vcc, exec, s[40:41]
	s_waitcnt vmcnt(8) lgkmcnt(0)
	v_pk_fma_f32 v[26:27], v[70:71], v[30:31], v[26:27]
	v_lshl_add_u64 v[30:31], v[94:95], 0, v[84:85]
	v_pk_fma_f32 v[28:29], v[72:73], v[32:33], v[28:29]
	v_lshl_add_u64 v[30:31], v[30:31], 2, s[44:45]
	global_store_dwordx4 v[30:31], v[26:29], off offset:256
	s_cbranch_vccnz .LBB0_1156
	s_mov_b64 s[2:3], 0

.LBB0_1160:
	s_or_b64 exec, exec, s[2:3]
	s_waitcnt lgkmcnt(0)
	ds_read_b128 v[26:29], v229 offset:2176
	s_mov_b64 s[2:3], -1
	s_and_b64 vcc, exec, s[40:41]
	s_waitcnt vmcnt(9) lgkmcnt(0)
	v_pk_fma_f32 v[22:23], v[70:71], v[26:27], v[22:23]
	v_lshl_add_u64 v[26:27], v[90:91], 0, v[84:85]
	v_pk_fma_f32 v[24:25], v[72:73], v[28:29], v[24:25]
	v_lshl_add_u64 v[26:27], v[26:27], 2, s[44:45]
	global_store_dwordx4 v[26:27], v[22:25], off offset:256
	s_cbranch_vccnz .LBB0_1162
	s_mov_b64 s[2:3], 0

.LBB0_1166:
	s_or_b64 exec, exec, s[2:3]
	s_waitcnt lgkmcnt(0)
	ds_read_b128 v[22:25], v229 offset:3264
	s_mov_b64 s[2:3], -1
	s_and_b64 vcc, exec, s[40:41]
	s_waitcnt vmcnt(10) lgkmcnt(0)
	v_pk_fma_f32 v[18:19], v[70:71], v[22:23], v[18:19]
	v_lshl_add_u64 v[22:23], v[86:87], 0, v[84:85]
	v_pk_fma_f32 v[20:21], v[72:73], v[24:25], v[20:21]
	v_lshl_add_u64 v[22:23], v[22:23], 2, s[44:45]
	global_store_dwordx4 v[22:23], v[18:21], off offset:256
	s_cbranch_vccnz .LBB0_1168
	s_mov_b64 s[2:3], 0

.LBB0_1172:
	s_or_b64 exec, exec, s[2:3]
	s_waitcnt lgkmcnt(0)
	ds_read_b128 v[18:21], v229 offset:4352
	s_mov_b64 s[2:3], -1
	s_and_b64 vcc, exec, s[40:41]
	s_waitcnt vmcnt(11) lgkmcnt(0)
	v_pk_fma_f32 v[14:15], v[70:71], v[18:19], v[14:15]
	v_lshl_add_u64 v[18:19], v[82:83], 0, v[84:85]
	v_pk_fma_f32 v[16:17], v[72:73], v[20:21], v[16:17]
	v_lshl_add_u64 v[18:19], v[18:19], 2, s[44:45]
	global_store_dwordx4 v[18:19], v[14:17], off offset:256
	s_cbranch_vccnz .LBB0_1174
	s_mov_b64 s[2:3], 0

.LBB0_1178:
	s_or_b64 exec, exec, s[2:3]
	s_waitcnt lgkmcnt(0)
	ds_read_b128 v[14:17], v229 offset:5440
	s_mov_b64 s[2:3], -1
	s_and_b64 vcc, exec, s[40:41]
	s_waitcnt vmcnt(12) lgkmcnt(0)
	v_pk_fma_f32 v[10:11], v[70:71], v[14:15], v[10:11]
	v_lshl_add_u64 v[14:15], v[78:79], 0, v[84:85]
	v_pk_fma_f32 v[12:13], v[72:73], v[16:17], v[12:13]
	v_lshl_add_u64 v[14:15], v[14:15], 2, s[44:45]
	global_store_dwordx4 v[14:15], v[10:13], off offset:256
	s_cbranch_vccnz .LBB0_1180
	s_mov_b64 s[2:3], 0

.LBB0_1184:
	s_or_b64 exec, exec, s[2:3]
	s_waitcnt lgkmcnt(0)
	ds_read_b128 v[10:13], v229 offset:6528
	s_mov_b64 s[2:3], -1
	s_and_b64 vcc, exec, s[40:41]
	s_waitcnt vmcnt(13) lgkmcnt(0)
	v_pk_fma_f32 v[6:7], v[70:71], v[10:11], v[6:7]
	v_lshl_add_u64 v[10:11], v[74:75], 0, v[84:85]
	v_pk_fma_f32 v[8:9], v[72:73], v[12:13], v[8:9]
	v_lshl_add_u64 v[10:11], v[10:11], 2, s[44:45]
	global_store_dwordx4 v[10:11], v[6:9], off offset:256
	s_cbranch_vccnz .LBB0_1186
	s_mov_b64 s[2:3], 0

.LBB0_1190:
	s_or_b64 exec, exec, s[2:3]
	s_waitcnt lgkmcnt(0)
	ds_read_b128 v[6:9], v229 offset:7616
	v_lshl_add_u64 v[10:11], v[76:77], 0, v[84:85]
	s_and_b64 vcc, exec, s[40:41]
	v_lshl_add_u64 v[10:11], v[10:11], 2, s[44:45]
	s_mov_b64 s[2:3], -1
	s_waitcnt vmcnt(14) lgkmcnt(0)
	v_pk_fma_f32 v[4:5], v[72:73], v[8:9], v[4:5]
	v_pk_fma_f32 v[2:3], v[70:71], v[6:7], v[2:3]
	global_store_dwordx4 v[10:11], v[2:5], off offset:256
	s_cbranch_vccnz .LBB0_1192
	s_mov_b64 s[2:3], 0
